# M2 first MFMA block: 8 ds_reads batched ahead of MFMAs (on top of rg A-frag row-load ring)
# baseline (speedup 1.0000x reference)
.LBB0_177:
	s_cmp_lg_u32 s12, 0x7c0000
	s_cselect_b32 s56, s18, 31
	s_add_u32 s14, s8, s56
	s_addc_u32 s15, s9, 0
	s_waitcnt vmcnt(0)
	v_mov_b64_e32 v[66:67], v[14:15]
	s_lshl_b64 s[20:21], s[14:15], 13
	s_lshl_b64 s[14:15], s[14:15], 14
	v_mov_b64_e32 v[64:65], v[12:13]
	v_lshl_add_u64 v[12:13], v[82:83], 0, s[14:15]
	v_lshl_add_u64 v[48:49], v[84:85], 0, s[14:15]
	s_lshl_b64 s[14:15], s[56:57], 2
	s_add_u32 s14, s10, s14
	v_mov_b32_e32 v127, s21
	v_or_b32_e32 v126, s20, v102
	v_mov_b32_e32 v129, s21
	v_or_b32_e32 v128, s20, v104
	v_mov_b64_e32 v[70:71], v[10:11]
	v_mov_b64_e32 v[74:75], v[6:7]
	v_mov_b64_e32 v[78:79], v[2:3]
	v_lshl_add_u64 v[52:53], v[86:87], 0, s[20:21]
	s_addc_u32 s15, s11, s15
	v_lshl_add_u64 v[126:127], v[126:127], 2, s[82:83]
	v_lshl_add_u64 v[128:129], v[128:129], 2, s[82:83]
	v_mov_b64_e32 v[68:69], v[8:9]
	v_mov_b64_e32 v[72:73], v[4:5]
	v_mov_b64_e32 v[76:77], v[0:1]
	global_load_dwordx4 v[0:3], v[12:13], off
	global_load_dwordx4 v[4:7], v[12:13], off offset:64
	global_load_dwordx4 v[8:11], v[12:13], off offset:128
	s_nop 0
	global_load_dwordx4 v[12:15], v[12:13], off offset:192
	s_nop 0
	global_load_dwordx4 v[40:43], v[48:49], off
	global_load_dwordx4 v[44:47], v[52:53], off
	s_nop 0
	global_load_dwordx4 v[48:51], v[48:49], off offset:64
	s_nop 0
	global_load_dwordx4 v[52:55], v[52:53], off offset:64
	v_mov_b32_e32 v131, s21
	global_load_dword v101, v145, s[14:15]
	v_or_b32_e32 v130, s20, v108
	global_load_dword v126, v[126:127], off
	v_lshl_add_u64 v[130:131], v[130:131], 2, s[82:83]
	global_load_dword v127, v[128:129], off
	v_mov_b32_e32 v129, s21
	v_or_b32_e32 v128, s20, v106
	v_lshl_add_u64 v[128:129], v[128:129], 2, s[82:83]
	global_load_dword v128, v[128:129], off
	v_mov_b32_e32 v133, s21
	global_load_dword v129, v[130:131], off
	v_mov_b32_e32 v131, s21
	v_or_b32_e32 v130, s20, v110
	v_or_b32_e32 v132, s20, v112
	v_lshl_add_u64 v[130:131], v[130:131], 2, s[82:83]
	v_lshl_add_u64 v[132:133], v[132:133], 2, s[82:83]
	global_load_dword v130, v[130:131], off
	v_mov_b32_e32 v135, s21
	global_load_dword v131, v[132:133], off
	v_mov_b32_e32 v133, s21
	v_or_b32_e32 v132, s20, v114
	v_or_b32_e32 v134, s20, v116
	v_lshl_add_u64 v[132:133], v[132:133], 2, s[82:83]
	v_lshl_add_u64 v[134:135], v[134:135], 2, s[82:83]
	global_load_dword v132, v[132:133], off
	v_add_u32_e32 v142, v81, v109
	global_load_dword v133, v[134:135], off
	ds_read_b128 v[162:165], v142
	ds_read_b128 v[166:169], v142 offset:4352
	ds_read_b128 v[172:175], v142 offset:64
	ds_read_b128 v[176:179], v142 offset:4416
	ds_read_b128 v[180:183], v142 offset:128
	ds_read_b128 v[184:187], v142 offset:4480
	ds_read_b128 v[192:195], v142 offset:192
	ds_read_b128 v[212:215], v142 offset:4544
	s_andn2_b64 vcc, exec, s[2:3]
	s_waitcnt lgkmcnt(6)
	v_mfma_f32_16x16x32_bf16 v[134:137], v[76:79], v[162:165], 0
	v_mfma_f32_16x16x32_bf16 v[138:141], v[76:79], v[166:169], 0
	s_waitcnt lgkmcnt(4)
	v_mfma_f32_16x16x32_bf16 v[134:137], v[72:75], v[172:175], v[134:137]
	v_mfma_f32_16x16x32_bf16 v[138:141], v[72:75], v[176:179], v[138:141]
	s_waitcnt lgkmcnt(2)
	v_mfma_f32_16x16x32_bf16 v[134:137], v[68:71], v[180:183], v[134:137]
	v_mfma_f32_16x16x32_bf16 v[138:141], v[68:71], v[184:187], v[138:141]
	s_waitcnt lgkmcnt(0)
	v_mfma_f32_16x16x32_bf16 v[72:75], v[64:67], v[192:195], v[134:137]
	v_mfma_f32_16x16x32_bf16 v[76:79], v[64:67], v[212:215], v[138:141]
	s_nop 7
	s_cbranch_vccnz .LBB0_179
	s_waitcnt vmcnt(25)
	v_sub_f32_e32 v56, v56, v72
	s_waitcnt vmcnt(24)
	v_sub_f32_e32 v57, v57, v73
	v_cvt_pk_bf16_f32 v56, v56, v57
	s_waitcnt vmcnt(23)
	v_sub_f32_e32 v57, v58, v74
	s_waitcnt vmcnt(22)
	v_sub_f32_e32 v58, v59, v75
	v_cvt_pk_bf16_f32 v57, v57, v58
	ds_write_b64 v117, v[56:57] offset:8704
	s_waitcnt vmcnt(21)
	v_sub_f32_e32 v56, v60, v76
	s_waitcnt vmcnt(20)
	v_sub_f32_e32 v57, v61, v77
	v_cvt_pk_bf16_f32 v56, v56, v57
	s_waitcnt vmcnt(18)
	v_sub_f32_e32 v57, v62, v78
	s_waitcnt vmcnt(17)
	v_sub_f32_e32 v58, v63, v79
	v_cvt_pk_bf16_f32 v57, v57, v58
	ds_write_b64 v117, v[56:57] offset:11008
